# speedup vs baseline: 1.0378x; 1.0162x over previous
.Lp8a_eb_ok:
	s_cmp_ge_i32 s0, s9
	s_cbranch_scc1 .LBB0_843
	ds_read_b32 v0, v169
	s_lshl_b32 s1, s13, 2
	s_and_b32 s34, s1, 0x300
	v_mov_b32_e32 v118, v144
	v_readlane_b32 s44, v209, 0
	s_waitcnt lgkmcnt(0)
	v_readfirstlane_b32 s1, v0
	s_cmp_gt_i32 s1, s0
	s_cselect_b32 s10, 0, 32
	s_lshl_b32 s15, s10, 2
	s_or_b32 s15, s15, 0x13040
	v_mov_b32_e32 v0, s15
	ds_read_b32 v0, v0
	s_or_b32 s11, s10, 16
	v_readlane_b32 s45, v209, 1
	v_readlane_b32 s47, v209, 3
	v_readlane_b32 s46, v209, 2
	s_waitcnt lgkmcnt(0)
	v_readfirstlane_b32 s15, v0
	s_cmp_gt_i32 s15, s0
	s_cselect_b32 s10, s10, s11
	s_lshl_b32 s15, s10, 2
	s_or_b32 s15, s15, 0x13020
	v_mov_b32_e32 v0, s15
	ds_read_b32 v0, v0
	s_or_b32 s11, s10, 8
	v_mov_b32_e32 v6, s45
	v_mov_b32_e32 v25, v1
	s_mov_b64 s[38:39], 0x2000
	s_waitcnt lgkmcnt(0)
	v_readfirstlane_b32 s15, v0
	s_cmp_gt_i32 s15, s0
	s_cselect_b32 s10, s10, s11
	s_lshl_b32 s15, s10, 2
	s_or_b32 s15, s15, 0x13010
	v_mov_b32_e32 v0, s15
	ds_read_b32 v0, v0
	s_or_b32 s11, s10, 4
	s_mov_b32 s1, 0
	v_readlane_b32 s48, v209, 4
	v_readlane_b32 s49, v209, 5
	s_waitcnt lgkmcnt(0)
	v_readfirstlane_b32 s15, v0
	s_cmp_gt_i32 s15, s0
	s_cselect_b32 s10, s10, s11
	s_lshl_b32 s15, s10, 2
	s_add_i32 s15, s15, 0x13008
	v_mov_b32_e32 v0, s15
	ds_read_b32 v0, v0
	s_add_i32 s11, s10, 2
	v_readlane_b32 s50, v209, 6
	v_readlane_b32 s51, v209, 7
	s_waitcnt lgkmcnt(0)
	v_readfirstlane_b32 s15, v0
	s_cmp_gt_i32 s15, s0
	s_cselect_b32 s10, s10, s11
	s_lshl_b32 s15, s10, 2
	s_add_i32 s15, s15, 0x13004
	v_mov_b32_e32 v0, s15
	ds_read_b32 v0, v0
	s_add_i32 s11, s10, 1
	s_waitcnt lgkmcnt(0)
	v_readfirstlane_b32 s15, v0
	s_cmp_gt_i32 s15, s0
	s_cselect_b32 s16, s10, s11
	s_lshl_b32 s10, s16, 2
	s_add_i32 s10, s10, 0x13000
	v_mov_b32_e32 v0, s10
	ds_read_b32 v2, v0
	s_lshl_b64 s[10:11], s[16:17], 16
	s_add_u32 s10, s56, s10
	s_addc_u32 s11, s57, s11
	s_waitcnt lgkmcnt(0)
	v_sub_u32_e32 v2, s0, v2
	v_lshlrev_b32_e32 v2, 7, v2
	v_ashrrev_i32_e32 v3, 31, v2
	v_lshlrev_b64 v[4:5], 2, v[2:3]
	v_and_b32_e32 v3, 8, v118
	v_cmp_eq_u32_e32 vcc, 0, v3
	v_mov_b32_e32 v3, s47
	v_lshl_add_u64 v[4:5], s[10:11], 0, v[4:5]
	v_cndmask_b32_e32 v23, v3, v6, vcc
	v_mov_b32_e32 v3, s46
	v_mov_b32_e32 v6, s44
	v_cndmask_b32_e32 v22, v3, v6, vcc
	v_ashrrev_i32_e32 v6, 3, v118
	v_ashrrev_i32_e32 v7, 31, v6
	v_lshl_add_u64 v[4:5], v[6:7], 2, v[4:5]
	global_load_dword v3, v[4:5], off
	global_load_dword v8, v[4:5], off offset:256
	v_add_u32_e32 v10, v6, v2
	global_load_dword v6, v[4:5], off offset:128
	ds_read_b32 v0, v0 offset:260
	global_load_dword v4, v[4:5], off offset:384
	v_add_u32_e32 v7, 32, v10
	s_add_i32 s10, s16, s8
	v_add_u32_e32 v9, 64, v10
	s_waitcnt lgkmcnt(0)
	v_cmp_lt_i32_e32 vcc, v10, v0
	s_ashr_i32 s11, s10, 31
	s_lshl_b32 s15, s14, 3
	v_add_u32_e32 v5, 0x60, v10
	s_lshl_b64 s[10:11], s[10:11], 20
	s_and_b32 s15, s15, 0xc0
	v_lshl_add_u64 v[10:11], v[22:23], 0, s[10:11]
	s_lshl_b32 s10, s15, 2
	s_mov_b32 s11, s17
	v_lshl_add_u64 v[10:11], v[10:11], 0, s[10:11]
	s_movk_i32 s11, 0x4000
	s_waitcnt vmcnt(3)
	v_ashrrev_i32_e32 v2, 1, v3
	v_cndmask_b32_e32 v2, 0, v2, vcc
	v_cmp_lt_i32_e32 vcc, v7, v0
	s_waitcnt vmcnt(1)
	v_ashrrev_i32_e32 v6, 1, v6
	v_ashrrev_i32_e32 v8, 1, v8
	v_cndmask_b32_e32 v6, 0, v6, vcc
	v_cmp_lt_i32_e32 vcc, v9, v0
	v_ashrrev_i32_e32 v3, 31, v2
	v_lshlrev_b64 v[28:29], 11, v[2:3]
	v_cndmask_b32_e32 v8, 0, v8, vcc
	v_cmp_lt_i32_e32 vcc, v5, v0
	s_waitcnt vmcnt(0)
	v_ashrrev_i32_e32 v0, 1, v4
	v_lshl_add_u64 v[2:3], s[4:5], 0, v[28:29]
	v_cndmask_b32_e32 v4, 0, v0, vcc
	v_lshlrev_b32_e32 v0, 3, v118
	v_and_b32_e32 v24, 0x80, v0
	v_lshl_add_u64 v[10:11], v[10:11], 0, v[24:25]
	v_mov_b32_e32 v25, v144
	v_lshlrev_b32_e32 v0, 4, v118
	v_and_b32_e32 v0, 0x70, v0
	v_ashrrev_i32_e32 v36, 5, v25
	v_ashrrev_i32_e32 v37, 31, v36
	v_lshl_add_u64 v[10:11], v[10:11], 0, v[0:1]
	v_lshlrev_b64 v[26:27], 10, v[36:37]
	v_lshlrev_b32_e32 v0, 4, v25
	v_ashrrev_i32_e32 v7, 31, v6
	v_lshl_add_u64 v[90:91], v[10:11], 0, v[26:27]
	v_and_b32_e32 v0, 0x70, v0
	v_lshlrev_b64 v[30:31], 11, v[6:7]
	v_lshl_add_u64 v[82:83], v[2:3], 0, v[0:1]
	v_add_co_u32_e32 v2, vcc, s93, v90
	v_lshl_add_u64 v[6:7], s[4:5], 0, v[30:31]
	s_nop 0
	v_addc_co_u32_e32 v3, vcc, 0, v91, vcc
	v_lshl_add_u64 v[84:85], v[6:7], 0, v[0:1]
	v_add_co_u32_e32 v6, vcc, s11, v90
	s_movk_i32 s11, 0x6000
	s_nop 0
	v_addc_co_u32_e32 v7, vcc, 0, v91, vcc
	v_add_co_u32_e32 v10, vcc, s11, v90
	v_ashrrev_i32_e32 v5, 31, v4
	s_nop 0
	v_addc_co_u32_e32 v11, vcc, 0, v91, vcc
	v_add_co_u32_e32 v14, vcc, s72, v90
	v_ashrrev_i32_e32 v9, 31, v8
	v_lshlrev_b64 v[34:35], 11, v[4:5]
	global_load_dwordx4 v[18:21], v[90:91], off
	v_addc_co_u32_e32 v15, vcc, 0, v91, vcc
	s_mov_b32 s11, 0xa000
	v_lshlrev_b64 v[32:33], 11, v[8:9]
	v_lshl_add_u64 v[4:5], s[4:5], 0, v[34:35]
	v_add_co_u32_e32 v38, vcc, s11, v90
	v_lshl_add_u64 v[8:9], s[4:5], 0, v[32:33]
	v_lshl_add_u64 v[88:89], v[4:5], 0, v[0:1]
	global_load_dwordx4 v[2:5], v[2:3], off
	v_addc_co_u32_e32 v39, vcc, 0, v91, vcc
	s_mov_b32 s11, 0xc000
	v_lshl_add_u64 v[86:87], v[8:9], 0, v[0:1]
	global_load_dwordx4 v[6:9], v[6:7], off
	v_add_co_u32_e32 v42, vcc, s11, v90
	global_load_dwordx4 v[10:13], v[10:11], off
	s_nop 0
	v_addc_co_u32_e32 v43, vcc, 0, v91, vcc
	global_load_dwordx4 v[14:17], v[14:15], off
	s_mov_b32 s11, 0xe000
	global_load_dwordx4 v[38:41], v[38:39], off
	v_add_co_u32_e32 v46, vcc, s11, v90
	global_load_dwordx4 v[42:45], v[42:43], off
	s_nop 0
	v_addc_co_u32_e32 v47, vcc, 0, v91, vcc
	global_load_dwordx4 v[46:49], v[46:47], off
	s_nop 0
	global_load_dwordx4 v[50:53], v[82:83], off
	global_load_dwordx4 v[54:57], v[84:85], off
	global_load_dwordx4 v[58:61], v[86:87], off
	global_load_dwordx4 v[62:65], v[88:89], off
	v_lshlrev_b32_e32 v66, 2, v25
	v_and_b32_e32 v67, 0x7c, v66
	v_lshl_add_u64 v[92:93], v[90:91], 0, s[38:39]
	s_mov_b64 s[38:39], 0x4000
	v_lshl_add_u64 v[94:95], v[90:91], 0, s[38:39]
	s_mov_b64 s[38:39], 0x6000
	v_lshl_add_u64 v[96:97], v[90:91], 0, s[38:39]
	s_mov_b64 s[38:39], 0x8000
	v_lshl_add_u64 v[98:99], v[90:91], 0, s[38:39]
	s_mov_b64 s[38:39], 0xa000
	v_lshl_add_u64 v[100:101], v[90:91], 0, s[38:39]
	s_mov_b64 s[38:39], 0xc000
	v_lshrrev_b32_e32 v37, 3, v25
	v_lshl_add_u64 v[104:105], v[90:91], 0, s[38:39]
	s_mov_b64 s[38:39], 0xe000
	s_movk_i32 s11, 0x90
	v_readfirstlane_b32 s10, v25
	v_lshl_add_u64 v[106:107], v[90:91], 0, s[38:39]
	v_mad_u64_u32 v[102:103], s[38:39], v37, s11, v[0:1]
	v_and_b32_e32 v0, 31, v25
	v_and_or_b32 v0, s10, 64, v0
	v_lshlrev_b32_e32 v68, 3, v25
	s_ashr_i32 s10, s10, 1
	s_andn2_b32 s10, s10, 63
	s_waitcnt vmcnt(11)
	v_cvt_pk_bf16_f32 v18, v18, v19
	v_cvt_pk_bf16_f32 v19, v20, v21
	v_lshlrev_b32_e32 v20, 7, v36
	v_and_b32_e32 v21, 0x60, v25
	v_bitop3_b32 v120, v67, v20, v21 bitop3:0xde
	v_lshlrev_b32_e32 v119, 1, v120
	s_waitcnt vmcnt(10)
	v_cvt_pk_bf16_f32 v2, v2, v3
	v_cvt_pk_bf16_f32 v3, v4, v5
	ds_write2st64_b64 v119, v[18:19], v[2:3] offset1:4
	s_waitcnt vmcnt(9)
	v_cvt_pk_bf16_f32 v2, v6, v7
	v_cvt_pk_bf16_f32 v3, v8, v9
	s_waitcnt vmcnt(8)
	v_cvt_pk_bf16_f32 v4, v10, v11
	v_cvt_pk_bf16_f32 v5, v12, v13
	ds_write2st64_b64 v119, v[2:3], v[4:5] offset0:8 offset1:12
	s_waitcnt vmcnt(7)
	v_cvt_pk_bf16_f32 v2, v14, v15
	v_cvt_pk_bf16_f32 v3, v16, v17
	s_waitcnt vmcnt(6)
	v_cvt_pk_bf16_f32 v4, v38, v39
	v_cvt_pk_bf16_f32 v5, v40, v41
	ds_write2st64_b64 v119, v[2:3], v[4:5] offset0:16 offset1:20
	s_waitcnt vmcnt(5)
	v_cvt_pk_bf16_f32 v2, v42, v43
	v_cvt_pk_bf16_f32 v3, v44, v45
	s_waitcnt vmcnt(4)
	v_cvt_pk_bf16_f32 v4, v46, v47
	v_cvt_pk_bf16_f32 v5, v48, v49
	ds_write2st64_b64 v119, v[2:3], v[4:5] offset0:24 offset1:28
	v_lshrrev_b32_e32 v2, 1, v25
	v_and_b32_e32 v2, 16, v2
	v_mad_u32_u24 v103, v0, s11, v2
	v_and_b32_e32 v0, 16, v25
	v_and_or_b32 v0, v66, 12, v0
	v_and_b32_e32 v3, 0x60, v68
	v_or_b32_e32 v2, s10, v0
	v_bitop3_b32 v122, v0, v3, s10 bitop3:0x36
	v_readlane_b32 s10, v207, 19
	v_readlane_b32 s11, v207, 20
	v_bitop3_b32 v121, v2, v3, 32 bitop3:0x36
	v_and_b32_e32 v5, 7, v118
	v_lshl_add_u64 v[108:109], s[10:11], 0, v[28:29]
	v_lshl_add_u64 v[110:111], s[10:11], 0, v[30:31]
	v_lshl_add_u64 v[112:113], s[10:11], 0, v[32:33]
	v_lshl_add_u64 v[114:115], s[10:11], 0, v[34:35]
	v_readlane_b32 s10, v207, 25
	s_add_i32 s10, s10, s16
	s_ashr_i32 s11, s10, 31
	s_lshl_b64 s[10:11], s[10:11], 20
	v_lshl_add_u64 v[2:3], s[10:11], 0, v[26:27]
	v_or_b32_e32 v2, s34, v2
	v_lshlrev_b32_e32 v5, 4, v5
	v_lshlrev_b32_e32 v0, 5, v25
	v_or3_b32 v2, v2, v24, v5
	v_and_b32_e32 v4, 0x580, v0
	v_and_b32_e32 v0, 7, v25
	v_lshl_add_u64 v[116:117], v[22:23], 0, v[2:3]
	v_mov_b32_e32 v2, 0
	s_waitcnt vmcnt(3)
	ds_write_b128 v102, v[50:53] offset:32768
	s_waitcnt vmcnt(2)
	ds_write_b128 v102, v[54:57] offset:37376
	s_waitcnt vmcnt(1)
	ds_write_b128 v102, v[58:61] offset:41984
	s_waitcnt vmcnt(0)
	ds_write_b128 v102, v[62:65] offset:46592
	v_lshlrev_b32_e32 v0, 4, v0
	s_mov_b64 s[10:11], 0
	v_lshlrev_b32_e32 v123, 1, v4
	v_mov_b32_e32 v3, v2
	v_mov_b32_e32 v4, v2
	v_mov_b32_e32 v5, v2
	v_mov_b32_e32 v6, v2
	v_mov_b32_e32 v7, v2
	v_mov_b32_e32 v8, v2
	v_mov_b32_e32 v9, v2
	v_mov_b32_e32 v10, v2
	v_mov_b32_e32 v11, v2
	v_mov_b32_e32 v12, v2
	v_mov_b32_e32 v13, v2
	v_mov_b32_e32 v14, v2
	v_mov_b32_e32 v15, v2
	v_mov_b32_e32 v16, v2
	v_mov_b32_e32 v17, v2
	v_mov_b32_e32 v34, v2
	v_mov_b32_e32 v35, v2
	v_mov_b32_e32 v36, v2
	v_mov_b32_e32 v37, v2
	v_mov_b32_e32 v38, v2
	v_mov_b32_e32 v39, v2
	v_mov_b32_e32 v40, v2
	v_mov_b32_e32 v41, v2
	v_mov_b32_e32 v42, v2
	v_mov_b32_e32 v43, v2
	v_mov_b32_e32 v44, v2
	v_mov_b32_e32 v45, v2
	v_mov_b32_e32 v46, v2
	v_mov_b32_e32 v47, v2
	v_mov_b32_e32 v48, v2
	v_mov_b32_e32 v49, v2
	v_mov_b32_e32 v18, v2
	v_mov_b32_e32 v19, v2
	v_mov_b32_e32 v20, v2
	v_mov_b32_e32 v21, v2
	v_mov_b32_e32 v22, v2
	v_mov_b32_e32 v23, v2
	v_mov_b32_e32 v24, v2
	v_mov_b32_e32 v25, v2
	v_mov_b32_e32 v26, v2
	v_mov_b32_e32 v27, v2
	v_mov_b32_e32 v28, v2
	v_mov_b32_e32 v29, v2
	v_mov_b32_e32 v30, v2
	v_mov_b32_e32 v31, v2
	v_mov_b32_e32 v32, v2
	v_mov_b32_e32 v33, v2
	v_mov_b32_e32 v50, v2
	v_mov_b32_e32 v51, v2
	v_mov_b32_e32 v52, v2
	v_mov_b32_e32 v53, v2
	v_mov_b32_e32 v54, v2
	v_mov_b32_e32 v55, v2
	v_mov_b32_e32 v56, v2
	v_mov_b32_e32 v57, v2
	v_mov_b32_e32 v58, v2
	v_mov_b32_e32 v59, v2
	v_mov_b32_e32 v60, v2
	v_mov_b32_e32 v61, v2
	v_mov_b32_e32 v62, v2
	v_mov_b32_e32 v63, v2
	v_mov_b32_e32 v64, v2
	v_mov_b32_e32 v65, v2
	s_waitcnt lgkmcnt(0)
	s_barrier
	v_lshl_add_u64 v[66:67], v[116:117], 0, s[10:11]
	s_mov_b32 s16, 0x10000
	v_lshl_add_u64 v[124:125], v[66:67], 0, s[16:17]
	s_mov_b32 s16, 0x12000
	v_lshl_add_u64 v[128:129], v[66:67], 0, s[16:17]
	s_mov_b32 s16, 0x14000
	v_lshl_add_u64 v[132:133], v[66:67], 0, s[16:17]
	s_mov_b32 s16, 0x16000
	v_lshl_add_u64 v[136:137], v[66:67], 0, s[16:17]
	s_mov_b32 s16, 0x18000
	v_lshl_add_u64 v[140:141], v[66:67], 0, s[16:17]
	s_mov_b32 s16, 0x1a000
	v_lshl_add_u64 v[150:151], v[66:67], 0, s[16:17]
	s_mov_b32 s16, 0x1c000
	v_lshl_add_u64 v[154:155], v[66:67], 0, s[16:17]
	s_mov_b32 s16, 0x1e000
	v_lshl_add_u64 v[186:187], v[66:67], 0, s[16:17]
	v_lshl_add_u64 v[70:71], v[110:111], 0, v[0:1]
	v_lshl_add_u64 v[74:75], v[112:113], 0, v[0:1]
	v_lshl_add_u64 v[78:79], v[114:115], 0, v[0:1]
	v_lshl_add_u64 v[66:67], v[108:109], 0, v[0:1]
	global_load_dwordx4 v[66:69], v[66:67], off
	global_load_dwordx4 v[70:73], v[70:71], off
	global_load_dwordx4 v[74:77], v[74:75], off
	global_load_dwordx4 v[78:81], v[78:79], off
	global_load_dwordx4 v[124:127], v[124:125], off
	global_load_dwordx4 v[128:131], v[128:129], off
	global_load_dwordx4 v[132:135], v[132:133], off
	global_load_dwordx4 v[136:139], v[136:137], off
	global_load_dwordx4 v[140:143], v[140:141], off
	global_load_dwordx4 v[150:153], v[150:151], off
	global_load_dwordx4 v[154:157], v[154:155], off
	global_load_dwordx4 v[186:189], v[186:187], off
	s_and_b32 s16, s1, 1
.LBB0_846:
	v_lshl_add_u64 v[210:211], v[116:117], 0, s[10:11]
	s_mov_b32 s16, 0x20000
	v_lshl_add_u64 v[226:227], v[210:211], 0, s[16:17]
	s_mov_b32 s16, 0x22000
	v_lshl_add_u64 v[230:231], v[210:211], 0, s[16:17]
	s_mov_b32 s16, 0x24000
	v_lshl_add_u64 v[234:235], v[210:211], 0, s[16:17]
	s_mov_b32 s16, 0x26000
	v_lshl_add_u64 v[238:239], v[210:211], 0, s[16:17]
	s_mov_b32 s16, 0x28000
	v_lshl_add_u64 v[242:243], v[210:211], 0, s[16:17]
	s_mov_b32 s16, 0x2a000
	v_lshl_add_u64 v[246:247], v[210:211], 0, s[16:17]
	s_mov_b32 s16, 0x2c000
	v_lshl_add_u64 v[250:251], v[210:211], 0, s[16:17]
	s_mov_b32 s16, 0x2e000
	v_lshl_add_u64 v[104:105], v[210:211], 0, s[16:17]
	v_lshl_add_u64 v[214:215], v[110:111], 0, v[0:1]
	v_lshl_add_u64 v[218:219], v[112:113], 0, v[0:1]
	v_lshl_add_u64 v[222:223], v[114:115], 0, v[0:1]
	v_lshl_add_u64 v[210:211], v[108:109], 0, v[0:1]
	global_load_dwordx4 v[210:213], v[210:211], off offset:128
	global_load_dwordx4 v[214:217], v[214:215], off offset:128
	global_load_dwordx4 v[218:221], v[218:219], off offset:128
	global_load_dwordx4 v[222:225], v[222:223], off offset:128
	global_load_dwordx4 v[226:229], v[226:227], off
	global_load_dwordx4 v[230:233], v[230:231], off
	global_load_dwordx4 v[234:237], v[234:235], off
	global_load_dwordx4 v[238:241], v[238:239], off
	global_load_dwordx4 v[242:245], v[242:243], off
	global_load_dwordx4 v[246:249], v[246:247], off
	global_load_dwordx4 v[250:253], v[250:251], off
	global_load_dwordx4 v[104:107], v[104:105], off
	s_and_b32 s16, s1, 1
	s_add_i32 s1, s1, 1
	s_lshl_b32 s34, s16, 14
	v_lshlrev_b32_e32 v158, 1, v122
	v_lshlrev_b32_e32 v202, 1, v121
	v_add3_u32 v158, s34, v158, v123
	v_add3_u32 v206, s34, v202, v123
	ds_read_b64_tr_b16 v[190:191], v158
	ds_read_b64_tr_b16 v[192:193], v158 offset:1024
	ds_read_b64_tr_b16 v[202:203], v206
	ds_read_b64_tr_b16 v[204:205], v206 offset:1024
	s_mul_i32 s35, s16, 0x4800
	v_add_u32_e32 v159, s35, v103
	ds_read_b128 v[194:197], v159 offset:32768
	ds_read_b128 v[198:201], v159 offset:37376
	s_waitcnt lgkmcnt(1)
	v_mfma_f32_32x32x16_bf16 v[50:65], v[190:193], v[194:197], v[50:65]
	s_waitcnt lgkmcnt(0)
	v_mfma_f32_32x32x16_bf16 v[18:33], v[190:193], v[198:201], v[18:33]
	v_mfma_f32_32x32x16_bf16 v[34:49], v[202:205], v[194:197], v[34:49]
	ds_read_b64_tr_b16 v[190:191], v158 offset:4096
	ds_read_b64_tr_b16 v[192:193], v158 offset:5120
	ds_read_b128 v[194:197], v159 offset:32800
	v_mfma_f32_32x32x16_bf16 v[2:17], v[202:205], v[198:201], v[2:17]
	ds_read_b128 v[198:201], v159 offset:37408
	ds_read_b64_tr_b16 v[202:203], v206 offset:4096
	ds_read_b64_tr_b16 v[204:205], v206 offset:5120
	s_waitcnt lgkmcnt(3)
	v_mfma_f32_32x32x16_bf16 v[50:65], v[190:193], v[194:197], v[50:65]
	s_waitcnt lgkmcnt(2)
	v_mfma_f32_32x32x16_bf16 v[18:33], v[190:193], v[198:201], v[18:33]
	s_waitcnt lgkmcnt(0)
	v_mfma_f32_32x32x16_bf16 v[34:49], v[202:205], v[194:197], v[34:49]
	ds_read_b64_tr_b16 v[190:191], v158 offset:8192
	ds_read_b64_tr_b16 v[192:193], v158 offset:9216
	ds_read_b128 v[194:197], v159 offset:32832
	v_mfma_f32_32x32x16_bf16 v[2:17], v[202:205], v[198:201], v[2:17]
	ds_read_b128 v[198:201], v159 offset:37440
	ds_read_b64_tr_b16 v[202:203], v206 offset:8192
	ds_read_b64_tr_b16 v[204:205], v206 offset:9216
	s_waitcnt lgkmcnt(3)
	v_mfma_f32_32x32x16_bf16 v[50:65], v[190:193], v[194:197], v[50:65]
	s_waitcnt lgkmcnt(2)
	v_mfma_f32_32x32x16_bf16 v[18:33], v[190:193], v[198:201], v[18:33]
	s_waitcnt lgkmcnt(0)
	v_mfma_f32_32x32x16_bf16 v[34:49], v[202:205], v[194:197], v[34:49]
	ds_read_b64_tr_b16 v[190:191], v158 offset:12288
	ds_read_b64_tr_b16 v[192:193], v158 offset:13312
	ds_read_b128 v[194:197], v159 offset:32864
	v_mfma_f32_32x32x16_bf16 v[2:17], v[202:205], v[198:201], v[2:17]
	ds_read_b128 v[198:201], v159 offset:37472
	ds_read_b64_tr_b16 v[202:203], v206 offset:12288
	ds_read_b64_tr_b16 v[204:205], v206 offset:13312
	s_waitcnt lgkmcnt(3)
	v_mfma_f32_32x32x16_bf16 v[50:65], v[190:193], v[194:197], v[50:65]
	s_waitcnt lgkmcnt(2)
	v_mfma_f32_32x32x16_bf16 v[18:33], v[190:193], v[198:201], v[18:33]
	s_waitcnt lgkmcnt(0)
	v_mfma_f32_32x32x16_bf16 v[34:49], v[202:205], v[194:197], v[34:49]
	v_mfma_f32_32x32x16_bf16 v[2:17], v[202:205], v[198:201], v[2:17]
	s_xor_b32 s16, s16, 1
	s_lshl_b32 s34, s16, 14
	s_waitcnt vmcnt(19)
	v_cvt_pk_bf16_f32 v124, v124, v125
	v_cvt_pk_bf16_f32 v125, v126, v127
	v_lshl_add_u32 v158, v120, 1, s34
	ds_write_b64 v158, v[124:125]
	s_waitcnt vmcnt(18)
	v_cvt_pk_bf16_f32 v124, v128, v129
	v_cvt_pk_bf16_f32 v125, v130, v131
	s_waitcnt vmcnt(17)
	v_cvt_pk_bf16_f32 v126, v132, v133
	v_cvt_pk_bf16_f32 v127, v134, v135
	ds_write2st64_b64 v158, v[124:125], v[126:127] offset0:4 offset1:8
	s_waitcnt vmcnt(16)
	v_cvt_pk_bf16_f32 v124, v136, v137
	v_cvt_pk_bf16_f32 v125, v138, v139
	s_waitcnt vmcnt(15)
	v_cvt_pk_bf16_f32 v126, v140, v141
	v_cvt_pk_bf16_f32 v127, v142, v143
	ds_write2st64_b64 v158, v[124:125], v[126:127] offset0:12 offset1:16
	s_waitcnt vmcnt(14)
	v_cvt_pk_bf16_f32 v124, v150, v151
	v_cvt_pk_bf16_f32 v125, v152, v153
	s_waitcnt vmcnt(13)
	v_cvt_pk_bf16_f32 v126, v154, v155
	v_cvt_pk_bf16_f32 v127, v156, v157
	s_add_u32 s10, s10, 0x10000
	ds_write2st64_b64 v158, v[124:125], v[126:127] offset0:20 offset1:24
	s_waitcnt vmcnt(12)
	v_cvt_pk_bf16_f32 v124, v186, v187
	v_cvt_pk_bf16_f32 v125, v188, v189
	s_mulk_i32 s16, 0x4800
	s_addc_u32 s11, s11, 0
	ds_write_b64 v158, v[124:125] offset:14336
	v_add_u32_e32 v124, s16, v102
	v_lshl_add_u64 v[108:109], v[108:109], 0, s[20:21]
	v_lshl_add_u64 v[110:111], v[110:111], 0, s[20:21]
	v_lshl_add_u64 v[112:113], v[112:113], 0, s[20:21]
	s_cmp_lg_u32 s10, 0xf0000
	v_lshl_add_u64 v[114:115], v[114:115], 0, s[20:21]
	ds_write_b128 v124, v[66:69] offset:32768
	ds_write_b128 v124, v[70:73] offset:37376
	ds_write_b128 v124, v[74:77] offset:41984
	ds_write_b128 v124, v[78:81] offset:46592
	s_waitcnt lgkmcnt(0)
	s_barrier
	v_lshl_add_u64 v[66:67], v[116:117], 0, s[10:11]
	s_mov_b32 s16, 0x20000
	v_lshl_add_u64 v[124:125], v[66:67], 0, s[16:17]
	s_mov_b32 s16, 0x22000
	v_lshl_add_u64 v[128:129], v[66:67], 0, s[16:17]
	s_mov_b32 s16, 0x24000
	v_lshl_add_u64 v[132:133], v[66:67], 0, s[16:17]
	s_mov_b32 s16, 0x26000
	v_lshl_add_u64 v[136:137], v[66:67], 0, s[16:17]
	s_mov_b32 s16, 0x28000
	v_lshl_add_u64 v[140:141], v[66:67], 0, s[16:17]
	s_mov_b32 s16, 0x2a000
	v_lshl_add_u64 v[150:151], v[66:67], 0, s[16:17]
	s_mov_b32 s16, 0x2c000
	v_lshl_add_u64 v[154:155], v[66:67], 0, s[16:17]
	s_mov_b32 s16, 0x2e000
	v_lshl_add_u64 v[186:187], v[66:67], 0, s[16:17]
	v_lshl_add_u64 v[70:71], v[110:111], 0, v[0:1]
	v_lshl_add_u64 v[74:75], v[112:113], 0, v[0:1]
	v_lshl_add_u64 v[78:79], v[114:115], 0, v[0:1]
	v_lshl_add_u64 v[66:67], v[108:109], 0, v[0:1]
	global_load_dwordx4 v[66:69], v[66:67], off offset:128
	global_load_dwordx4 v[70:73], v[70:71], off offset:128
	global_load_dwordx4 v[74:77], v[74:75], off offset:128
	global_load_dwordx4 v[78:81], v[78:79], off offset:128
	global_load_dwordx4 v[124:127], v[124:125], off
	global_load_dwordx4 v[128:131], v[128:129], off
	global_load_dwordx4 v[132:135], v[132:133], off
	global_load_dwordx4 v[136:139], v[136:137], off
	global_load_dwordx4 v[140:143], v[140:141], off
	global_load_dwordx4 v[150:153], v[150:151], off
	global_load_dwordx4 v[154:157], v[154:155], off
	global_load_dwordx4 v[186:189], v[186:187], off
	s_and_b32 s16, s1, 1
	s_add_i32 s1, s1, 1
	s_lshl_b32 s34, s16, 14
	v_lshlrev_b32_e32 v158, 1, v122
	v_lshlrev_b32_e32 v202, 1, v121
	v_add3_u32 v158, s34, v158, v123
	v_add3_u32 v206, s34, v202, v123
	ds_read_b64_tr_b16 v[190:191], v158
	ds_read_b64_tr_b16 v[192:193], v158 offset:1024
	ds_read_b64_tr_b16 v[202:203], v206
	ds_read_b64_tr_b16 v[204:205], v206 offset:1024
	s_mul_i32 s35, s16, 0x4800
	v_add_u32_e32 v159, s35, v103
	ds_read_b128 v[194:197], v159 offset:32768
	ds_read_b128 v[198:201], v159 offset:37376
	s_waitcnt lgkmcnt(1)
	v_mfma_f32_32x32x16_bf16 v[50:65], v[190:193], v[194:197], v[50:65]
	s_waitcnt lgkmcnt(0)
	v_mfma_f32_32x32x16_bf16 v[18:33], v[190:193], v[198:201], v[18:33]
	v_mfma_f32_32x32x16_bf16 v[34:49], v[202:205], v[194:197], v[34:49]
	ds_read_b64_tr_b16 v[190:191], v158 offset:4096
	ds_read_b64_tr_b16 v[192:193], v158 offset:5120
	ds_read_b128 v[194:197], v159 offset:32800
	v_mfma_f32_32x32x16_bf16 v[2:17], v[202:205], v[198:201], v[2:17]
	ds_read_b128 v[198:201], v159 offset:37408
	ds_read_b64_tr_b16 v[202:203], v206 offset:4096
	ds_read_b64_tr_b16 v[204:205], v206 offset:5120
	s_waitcnt lgkmcnt(3)
	v_mfma_f32_32x32x16_bf16 v[50:65], v[190:193], v[194:197], v[50:65]
	s_waitcnt lgkmcnt(2)
	v_mfma_f32_32x32x16_bf16 v[18:33], v[190:193], v[198:201], v[18:33]
	s_waitcnt lgkmcnt(0)
	v_mfma_f32_32x32x16_bf16 v[34:49], v[202:205], v[194:197], v[34:49]
	ds_read_b64_tr_b16 v[190:191], v158 offset:8192
	ds_read_b64_tr_b16 v[192:193], v158 offset:9216
	ds_read_b128 v[194:197], v159 offset:32832
	v_mfma_f32_32x32x16_bf16 v[2:17], v[202:205], v[198:201], v[2:17]
	ds_read_b128 v[198:201], v159 offset:37440
	ds_read_b64_tr_b16 v[202:203], v206 offset:8192
	ds_read_b64_tr_b16 v[204:205], v206 offset:9216
	s_waitcnt lgkmcnt(3)
	v_mfma_f32_32x32x16_bf16 v[50:65], v[190:193], v[194:197], v[50:65]
	s_waitcnt lgkmcnt(2)
	v_mfma_f32_32x32x16_bf16 v[18:33], v[190:193], v[198:201], v[18:33]
	s_waitcnt lgkmcnt(0)
	v_mfma_f32_32x32x16_bf16 v[34:49], v[202:205], v[194:197], v[34:49]
	ds_read_b64_tr_b16 v[190:191], v158 offset:12288
	ds_read_b64_tr_b16 v[192:193], v158 offset:13312
	ds_read_b128 v[194:197], v159 offset:32864
	v_mfma_f32_32x32x16_bf16 v[2:17], v[202:205], v[198:201], v[2:17]
	ds_read_b128 v[198:201], v159 offset:37472
	ds_read_b64_tr_b16 v[202:203], v206 offset:12288
	ds_read_b64_tr_b16 v[204:205], v206 offset:13312
	s_waitcnt lgkmcnt(3)
	v_mfma_f32_32x32x16_bf16 v[50:65], v[190:193], v[194:197], v[50:65]
	s_waitcnt lgkmcnt(2)
	v_mfma_f32_32x32x16_bf16 v[18:33], v[190:193], v[198:201], v[18:33]
	s_waitcnt lgkmcnt(0)
	v_mfma_f32_32x32x16_bf16 v[34:49], v[202:205], v[194:197], v[34:49]
	v_mfma_f32_32x32x16_bf16 v[2:17], v[202:205], v[198:201], v[2:17]
	s_xor_b32 s16, s16, 1
	s_lshl_b32 s34, s16, 14
	s_waitcnt vmcnt(19)
	v_cvt_pk_bf16_f32 v226, v226, v227
	v_cvt_pk_bf16_f32 v227, v228, v229
	v_lshl_add_u32 v158, v120, 1, s34
	ds_write_b64 v158, v[226:227]
	s_waitcnt vmcnt(18)
	v_cvt_pk_bf16_f32 v226, v230, v231
	v_cvt_pk_bf16_f32 v227, v232, v233
	s_waitcnt vmcnt(17)
	v_cvt_pk_bf16_f32 v228, v234, v235
	v_cvt_pk_bf16_f32 v229, v236, v237
	ds_write2st64_b64 v158, v[226:227], v[228:229] offset0:4 offset1:8
	s_waitcnt vmcnt(16)
	v_cvt_pk_bf16_f32 v226, v238, v239
	v_cvt_pk_bf16_f32 v227, v240, v241
	s_waitcnt vmcnt(15)
	v_cvt_pk_bf16_f32 v228, v242, v243
	v_cvt_pk_bf16_f32 v229, v244, v245
	ds_write2st64_b64 v158, v[226:227], v[228:229] offset0:12 offset1:16
	s_waitcnt vmcnt(14)
	v_cvt_pk_bf16_f32 v226, v246, v247
	v_cvt_pk_bf16_f32 v227, v248, v249
	s_waitcnt vmcnt(13)
	v_cvt_pk_bf16_f32 v228, v250, v251
	v_cvt_pk_bf16_f32 v229, v252, v253
	s_add_u32 s10, s10, 0x10000
	ds_write2st64_b64 v158, v[226:227], v[228:229] offset0:20 offset1:24
	s_waitcnt vmcnt(12)
	v_cvt_pk_bf16_f32 v226, v104, v105
	v_cvt_pk_bf16_f32 v227, v106, v107
	s_mulk_i32 s16, 0x4800
	s_addc_u32 s11, s11, 0
	ds_write_b64 v158, v[226:227] offset:14336
	v_add_u32_e32 v226, s16, v102
	v_lshl_add_u64 v[108:109], v[108:109], 0, s[20:21]
	v_lshl_add_u64 v[110:111], v[110:111], 0, s[20:21]
	v_lshl_add_u64 v[112:113], v[112:113], 0, s[20:21]
	s_cmp_lg_u32 s10, 0xe0000
	v_lshl_add_u64 v[114:115], v[114:115], 0, s[20:21]
	ds_write_b128 v226, v[210:213] offset:32768
	ds_write_b128 v226, v[214:217] offset:37376
	ds_write_b128 v226, v[218:221] offset:41984
	ds_write_b128 v226, v[222:225] offset:46592
	s_waitcnt lgkmcnt(0)
	s_barrier
	s_cbranch_scc1 .LBB0_846
	s_and_b32 s16, s1, 1
	s_add_i32 s1, s1, 1
	s_lshl_b32 s34, s16, 14
	v_lshlrev_b32_e32 v158, 1, v122
	v_lshlrev_b32_e32 v202, 1, v121
	v_add3_u32 v158, s34, v158, v123
	v_add3_u32 v206, s34, v202, v123
	ds_read_b64_tr_b16 v[190:191], v158
	ds_read_b64_tr_b16 v[192:193], v158 offset:1024
	ds_read_b64_tr_b16 v[202:203], v206
	ds_read_b64_tr_b16 v[204:205], v206 offset:1024
	s_mul_i32 s35, s16, 0x4800
	v_add_u32_e32 v159, s35, v103
	ds_read_b128 v[194:197], v159 offset:32768
	ds_read_b128 v[198:201], v159 offset:37376
	s_waitcnt lgkmcnt(1)
	v_mfma_f32_32x32x16_bf16 v[50:65], v[190:193], v[194:197], v[50:65]
	s_waitcnt lgkmcnt(0)
	v_mfma_f32_32x32x16_bf16 v[18:33], v[190:193], v[198:201], v[18:33]
	v_mfma_f32_32x32x16_bf16 v[34:49], v[202:205], v[194:197], v[34:49]
	ds_read_b64_tr_b16 v[190:191], v158 offset:4096
	ds_read_b64_tr_b16 v[192:193], v158 offset:5120
	ds_read_b128 v[194:197], v159 offset:32800
	v_mfma_f32_32x32x16_bf16 v[2:17], v[202:205], v[198:201], v[2:17]
	ds_read_b128 v[198:201], v159 offset:37408
	ds_read_b64_tr_b16 v[202:203], v206 offset:4096
	ds_read_b64_tr_b16 v[204:205], v206 offset:5120
	s_waitcnt lgkmcnt(3)
	v_mfma_f32_32x32x16_bf16 v[50:65], v[190:193], v[194:197], v[50:65]
	s_waitcnt lgkmcnt(2)
	v_mfma_f32_32x32x16_bf16 v[18:33], v[190:193], v[198:201], v[18:33]
	s_waitcnt lgkmcnt(0)
	v_mfma_f32_32x32x16_bf16 v[34:49], v[202:205], v[194:197], v[34:49]
	ds_read_b64_tr_b16 v[190:191], v158 offset:8192
	ds_read_b64_tr_b16 v[192:193], v158 offset:9216
	ds_read_b128 v[194:197], v159 offset:32832
	v_mfma_f32_32x32x16_bf16 v[2:17], v[202:205], v[198:201], v[2:17]
	ds_read_b128 v[198:201], v159 offset:37440
	ds_read_b64_tr_b16 v[202:203], v206 offset:8192
	ds_read_b64_tr_b16 v[204:205], v206 offset:9216
	s_waitcnt lgkmcnt(3)
	v_mfma_f32_32x32x16_bf16 v[50:65], v[190:193], v[194:197], v[50:65]
	s_waitcnt lgkmcnt(2)
	v_mfma_f32_32x32x16_bf16 v[18:33], v[190:193], v[198:201], v[18:33]
	s_waitcnt lgkmcnt(0)
	v_mfma_f32_32x32x16_bf16 v[34:49], v[202:205], v[194:197], v[34:49]
	ds_read_b64_tr_b16 v[190:191], v158 offset:12288
	ds_read_b64_tr_b16 v[192:193], v158 offset:13312
	ds_read_b128 v[194:197], v159 offset:32864
	v_mfma_f32_32x32x16_bf16 v[2:17], v[202:205], v[198:201], v[2:17]
	ds_read_b128 v[198:201], v159 offset:37472
	ds_read_b64_tr_b16 v[202:203], v206 offset:12288
	ds_read_b64_tr_b16 v[204:205], v206 offset:13312
	s_waitcnt lgkmcnt(3)
	v_mfma_f32_32x32x16_bf16 v[50:65], v[190:193], v[194:197], v[50:65]
	s_waitcnt lgkmcnt(2)
	v_mfma_f32_32x32x16_bf16 v[18:33], v[190:193], v[198:201], v[18:33]
	s_waitcnt lgkmcnt(0)
	v_mfma_f32_32x32x16_bf16 v[34:49], v[202:205], v[194:197], v[34:49]
	v_mfma_f32_32x32x16_bf16 v[2:17], v[202:205], v[198:201], v[2:17]
	s_xor_b32 s16, s16, 1
	s_lshl_b32 s34, s16, 14
	s_waitcnt vmcnt(7)
	v_cvt_pk_bf16_f32 v124, v124, v125
	v_cvt_pk_bf16_f32 v125, v126, v127
	v_lshl_add_u32 v158, v120, 1, s34
	ds_write_b64 v158, v[124:125]
	s_waitcnt vmcnt(6)
	v_cvt_pk_bf16_f32 v124, v128, v129
	v_cvt_pk_bf16_f32 v125, v130, v131
	s_waitcnt vmcnt(5)
	v_cvt_pk_bf16_f32 v126, v132, v133
	v_cvt_pk_bf16_f32 v127, v134, v135
	ds_write2st64_b64 v158, v[124:125], v[126:127] offset0:4 offset1:8
	s_waitcnt vmcnt(4)
	v_cvt_pk_bf16_f32 v124, v136, v137
	v_cvt_pk_bf16_f32 v125, v138, v139
	s_waitcnt vmcnt(3)
	v_cvt_pk_bf16_f32 v126, v140, v141
	v_cvt_pk_bf16_f32 v127, v142, v143
	ds_write2st64_b64 v158, v[124:125], v[126:127] offset0:12 offset1:16
	s_waitcnt vmcnt(2)
	v_cvt_pk_bf16_f32 v124, v150, v151
	v_cvt_pk_bf16_f32 v125, v152, v153
	s_waitcnt vmcnt(1)
	v_cvt_pk_bf16_f32 v126, v154, v155
	v_cvt_pk_bf16_f32 v127, v156, v157
	s_add_u32 s10, s10, 0x10000
	ds_write2st64_b64 v158, v[124:125], v[126:127] offset0:20 offset1:24
	s_waitcnt vmcnt(0)
	v_cvt_pk_bf16_f32 v124, v186, v187
	v_cvt_pk_bf16_f32 v125, v188, v189
	s_mulk_i32 s16, 0x4800
	s_addc_u32 s11, s11, 0
	ds_write_b64 v158, v[124:125] offset:14336
	v_add_u32_e32 v124, s16, v102
	v_lshl_add_u64 v[108:109], v[108:109], 0, s[20:21]
	v_lshl_add_u64 v[110:111], v[110:111], 0, s[20:21]
	v_lshl_add_u64 v[112:113], v[112:113], 0, s[20:21]
	s_cmp_lg_u32 s10, 0xf0000
	v_lshl_add_u64 v[114:115], v[114:115], 0, s[20:21]
	ds_write_b128 v124, v[66:69] offset:32768
	ds_write_b128 v124, v[70:73] offset:37376
	ds_write_b128 v124, v[74:77] offset:41984
	ds_write_b128 v124, v[78:81] offset:46592
	s_waitcnt lgkmcnt(0)
	s_barrier
	v_readfirstlane_b32 s10, v118
	v_and_b32_e32 v0, 31, v118
	v_lshl_add_u32 v116, v122, 1, v123
	v_lshl_add_u32 v117, v121, 1, v123
	ds_read_b64_tr_b16 v[124:125], v116 offset:16384
	ds_read_b64_tr_b16 v[126:127], v116 offset:17408
	ds_read_b128 v[128:131], v103 offset:51200
	ds_read_b128 v[132:135], v103 offset:55808
	ds_read_b64_tr_b16 v[120:121], v117 offset:16384
	ds_read_b64_tr_b16 v[122:123], v117 offset:17408
	s_waitcnt lgkmcnt(3)
	v_mfma_f32_32x32x16_bf16 v[50:65], v[124:127], v[128:131], v[50:65]
	s_waitcnt lgkmcnt(2)
	v_mfma_f32_32x32x16_bf16 v[18:33], v[124:127], v[132:135], v[18:33]
	s_waitcnt lgkmcnt(0)
	v_mfma_f32_32x32x16_bf16 v[34:49], v[120:123], v[128:131], v[34:49]
	v_mfma_f32_32x32x16_bf16 v[2:17], v[120:123], v[132:135], v[2:17]
	ds_read_b64_tr_b16 v[120:121], v116 offset:20480
	ds_read_b64_tr_b16 v[122:123], v116 offset:21504
	ds_read_b128 v[124:127], v103 offset:51232
	ds_read_b128 v[128:131], v103 offset:55840
	ds_read_b64_tr_b16 v[132:133], v117 offset:20480
	ds_read_b64_tr_b16 v[134:135], v117 offset:21504
	s_waitcnt lgkmcnt(3)
	v_mfma_f32_32x32x16_bf16 v[50:65], v[120:123], v[124:127], v[50:65]
	s_waitcnt lgkmcnt(2)
	v_mfma_f32_32x32x16_bf16 v[18:33], v[120:123], v[128:131], v[18:33]
	s_waitcnt lgkmcnt(0)
	v_mfma_f32_32x32x16_bf16 v[34:49], v[132:135], v[124:127], v[34:49]
	ds_read_b64_tr_b16 v[120:121], v116 offset:24576
	ds_read_b64_tr_b16 v[122:123], v116 offset:25600
	ds_read_b128 v[124:127], v103 offset:51264
	v_mfma_f32_32x32x16_bf16 v[2:17], v[132:135], v[128:131], v[2:17]
	ds_read_b128 v[128:131], v103 offset:55872
	ds_read_b64_tr_b16 v[132:133], v117 offset:24576
	ds_read_b64_tr_b16 v[134:135], v117 offset:25600
	s_waitcnt lgkmcnt(3)
	v_mfma_f32_32x32x16_bf16 v[50:65], v[120:123], v[124:127], v[50:65]
	s_waitcnt lgkmcnt(2)
	v_mfma_f32_32x32x16_bf16 v[18:33], v[120:123], v[128:131], v[18:33]
	s_waitcnt lgkmcnt(0)
	v_mfma_f32_32x32x16_bf16 v[34:49], v[132:135], v[124:127], v[34:49]
	ds_read_b64_tr_b16 v[120:121], v116 offset:28672
	ds_read_b64_tr_b16 v[122:123], v116 offset:29696
	ds_read_b128 v[124:127], v103 offset:51296
	v_mfma_f32_32x32x16_bf16 v[2:17], v[132:135], v[128:131], v[2:17]
	ds_read_b128 v[128:131], v103 offset:55904
	ds_read_b64_tr_b16 v[132:133], v117 offset:28672
	ds_read_b64_tr_b16 v[134:135], v117 offset:29696
	s_waitcnt lgkmcnt(3)
	v_mfma_f32_32x32x16_bf16 v[50:65], v[120:123], v[124:127], v[50:65]
	s_waitcnt lgkmcnt(2)
	v_mfma_f32_32x32x16_bf16 v[18:33], v[120:123], v[128:131], v[18:33]
	s_waitcnt lgkmcnt(0)
	v_mfma_f32_32x32x16_bf16 v[34:49], v[132:135], v[124:127], v[34:49]
	v_mfma_f32_32x32x16_bf16 v[2:17], v[132:135], v[128:131], v[2:17]
	v_mul_f32_e32 v67, 0xbfb8aa3b, v50
	v_exp_f32_e32 v67, v67
	v_mul_f32_e32 v68, 0xbfb8aa3b, v51
	v_exp_f32_e32 v69, v68
	s_ashr_i32 s1, s0, 31
	v_add_f32_e32 v67, 1.0, v67
	v_rcp_f32_e32 v68, v67
	v_add_f32_e32 v67, 1.0, v69
	v_mul_f32_e32 v69, 0xbfb8aa3b, v52
	v_exp_f32_e32 v70, v69
	v_mul_f32_e32 v69, 0xbfb8aa3b, v53
	v_exp_f32_e32 v71, v69
	v_rcp_f32_e32 v69, v67
	v_add_f32_e32 v67, 1.0, v70
	v_rcp_f32_e32 v70, v67
	v_add_f32_e32 v67, 1.0, v71
	v_rcp_f32_e32 v71, v67
	s_lshl_b64 s[0:1], s[0:1], 16
	s_add_u32 s0, s78, s0
	v_and_or_b32 v0, s10, 64, v0
	s_addc_u32 s1, s79, s1
	v_lshlrev_b32_e32 v0, 9, v0
	v_pk_mul_f32 v[50:51], v[50:51], v[68:69]
	v_lshl_add_u64 v[72:73], s[0:1], 0, v[0:1]
	v_pk_mul_f32 v[34:35], v[34:35], v[50:51]
	v_pk_mul_f32 v[50:51], v[52:53], v[70:71]
	v_mul_f32_e32 v0, 0xbfb8aa3b, v54
	v_pk_mul_f32 v[36:37], v[36:37], v[50:51]
	v_exp_f32_e32 v0, v0
	v_mul_f32_e32 v50, 0xbfb8aa3b, v55
	s_ashr_i32 s10, s10, 2
	v_exp_f32_e32 v53, v50
	s_andn2_b32 s10, s10, 31
	s_add_i32 s10, s10, s15
	v_lshrrev_b32_e32 v66, 3, v118
	v_and_or_b32 v66, v66, 4, s10
	v_add_f32_e32 v0, 1.0, v0
	v_ashrrev_i32_e32 v67, 31, v66
	v_rcp_f32_e32 v52, v0
	v_add_f32_e32 v0, 1.0, v53
	v_mul_f32_e32 v53, 0xbfb8aa3b, v56
	v_cvt_pk_bf16_f32 v34, v34, v35
	v_cvt_pk_bf16_f32 v35, v36, v37
	v_lshlrev_b64 v[36:37], 1, v[66:67]
	v_exp_f32_e32 v67, v53
	v_mul_f32_e32 v53, 0xbfb8aa3b, v57
	v_exp_f32_e32 v69, v53
	v_rcp_f32_e32 v53, v0
	v_add_f32_e32 v0, 1.0, v67
	v_rcp_f32_e32 v68, v0
	v_add_f32_e32 v0, 1.0, v69
	v_rcp_f32_e32 v69, v0
	v_lshl_add_u64 v[50:51], v[72:73], 0, v[36:37]
	s_waitcnt lgkmcnt(0)
	s_barrier
	global_store_dwordx2 v[50:51], v[34:35], off
	v_pk_mul_f32 v[34:35], v[54:55], v[52:53]
	v_mul_f32_e32 v0, 0xbfb8aa3b, v58
	v_pk_mul_f32 v[34:35], v[38:39], v[34:35]
	v_pk_mul_f32 v[38:39], v[56:57], v[68:69]
	v_cvt_pk_bf16_f32 v34, v34, v35
	v_pk_mul_f32 v[38:39], v[40:41], v[38:39]
	v_exp_f32_e32 v0, v0
	v_cvt_pk_bf16_f32 v35, v38, v39
	v_mul_f32_e32 v38, 0xbfb8aa3b, v59
	v_exp_f32_e32 v39, v38
	v_add_f32_e32 v0, 1.0, v0
	v_rcp_f32_e32 v38, v0
	global_store_dwordx2 v[50:51], v[34:35], off offset:16
	v_add_f32_e32 v0, 1.0, v39
	v_mul_f32_e32 v39, 0xbfb8aa3b, v60
	v_exp_f32_e32 v52, v39
	v_mul_f32_e32 v39, 0xbfb8aa3b, v61
	v_exp_f32_e32 v53, v39
	v_rcp_f32_e32 v39, v0
	v_add_f32_e32 v0, 1.0, v52
	v_rcp_f32_e32 v52, v0
	v_add_f32_e32 v0, 1.0, v53
	v_rcp_f32_e32 v53, v0
	v_pk_mul_f32 v[34:35], v[58:59], v[38:39]
	v_mul_f32_e32 v0, 0xbfb8aa3b, v62
	v_pk_mul_f32 v[34:35], v[42:43], v[34:35]
	v_pk_mul_f32 v[38:39], v[60:61], v[52:53]
	v_cvt_pk_bf16_f32 v34, v34, v35
	v_pk_mul_f32 v[38:39], v[44:45], v[38:39]
	v_exp_f32_e32 v0, v0
	v_cvt_pk_bf16_f32 v35, v38, v39
	v_mul_f32_e32 v38, 0xbfb8aa3b, v63
	v_exp_f32_e32 v39, v38
	v_add_f32_e32 v0, 1.0, v0
	v_rcp_f32_e32 v38, v0
	global_store_dwordx2 v[50:51], v[34:35], off offset:32
	v_add_f32_e32 v0, 1.0, v39
	v_mul_f32_e32 v39, 0xbfb8aa3b, v64
	v_exp_f32_e32 v44, v39
	v_mul_f32_e32 v39, 0xbfb8aa3b, v65
	v_exp_f32_e32 v45, v39
	v_rcp_f32_e32 v39, v0
	v_add_f32_e32 v0, 1.0, v44
	v_rcp_f32_e32 v44, v0
	v_add_f32_e32 v0, 1.0, v45
	v_rcp_f32_e32 v45, v0
	v_pk_mul_f32 v[34:35], v[62:63], v[38:39]
	v_mul_f32_e32 v0, 0xbfb8aa3b, v18
	v_pk_mul_f32 v[34:35], v[46:47], v[34:35]
	v_pk_mul_f32 v[38:39], v[64:65], v[44:45]
	v_cvt_pk_bf16_f32 v34, v34, v35
	v_pk_mul_f32 v[38:39], v[48:49], v[38:39]
	v_exp_f32_e32 v0, v0
	v_cvt_pk_bf16_f32 v35, v38, v39
	v_mul_f32_e32 v38, 0xbfb8aa3b, v19
	v_exp_f32_e32 v38, v38
	global_store_dwordx2 v[50:51], v[34:35], off offset:48
	v_add_f32_e32 v0, 1.0, v0
	v_mul_f32_e32 v35, 0xbfb8aa3b, v20
	v_rcp_f32_e32 v34, v0
	v_add_f32_e32 v0, 1.0, v38
	v_exp_f32_e32 v38, v35
	v_mul_f32_e32 v35, 0xbfb8aa3b, v21
	v_exp_f32_e32 v39, v35
	v_rcp_f32_e32 v35, v0
	v_add_f32_e32 v0, 1.0, v38
	v_rcp_f32_e32 v38, v0
	v_add_f32_e32 v0, 1.0, v39
	v_rcp_f32_e32 v39, v0
	v_pk_mul_f32 v[18:19], v[18:19], v[34:35]
	v_mul_f32_e32 v0, 0xbfb8aa3b, v22
	v_pk_mul_f32 v[2:3], v[2:3], v[18:19]
	v_pk_mul_f32 v[18:19], v[20:21], v[38:39]
	v_cvt_pk_bf16_f32 v2, v2, v3
	v_pk_mul_f32 v[4:5], v[4:5], v[18:19]
	v_exp_f32_e32 v0, v0
	v_cvt_pk_bf16_f32 v3, v4, v5
	v_mul_f32_e32 v4, 0xbfb8aa3b, v23
	v_exp_f32_e32 v19, v4
	v_add_f32_e32 v0, 1.0, v0
	v_rcp_f32_e32 v18, v0
	s_mov_b64 s[0:1], 0x4000
	v_add_f32_e32 v0, 1.0, v19
	v_mul_f32_e32 v19, 0xbfb8aa3b, v24
	v_exp_f32_e32 v20, v19
	v_mul_f32_e32 v19, 0xbfb8aa3b, v25
	v_exp_f32_e32 v21, v19
	v_rcp_f32_e32 v19, v0
	v_add_f32_e32 v0, 1.0, v20
	v_rcp_f32_e32 v20, v0
	v_add_f32_e32 v0, 1.0, v21
	v_rcp_f32_e32 v21, v0
	v_lshl_add_u64 v[46:47], v[72:73], 0, s[0:1]
	v_lshl_add_u64 v[4:5], v[46:47], 0, v[36:37]
	global_store_dwordx2 v[4:5], v[2:3], off
	v_pk_mul_f32 v[2:3], v[22:23], v[18:19]
	v_pk_mul_f32 v[4:5], v[24:25], v[20:21]
	v_pk_mul_f32 v[2:3], v[6:7], v[2:3]
	v_pk_mul_f32 v[4:5], v[8:9], v[4:5]
	v_mul_f32_e32 v0, 0xbfb8aa3b, v26
	v_cvt_pk_bf16_f32 v2, v2, v3
	v_cvt_pk_bf16_f32 v3, v4, v5
	v_exp_f32_e32 v0, v0
	v_mul_f32_e32 v4, 0xbfb8aa3b, v27
	v_exp_f32_e32 v7, v4
	v_or_b32_e32 v40, 8, v66
	v_add_f32_e32 v0, 1.0, v0
	v_rcp_f32_e32 v6, v0
	v_add_f32_e32 v0, 1.0, v7
	v_mul_f32_e32 v7, 0xbfb8aa3b, v28
	v_exp_f32_e32 v8, v7
	v_mul_f32_e32 v7, 0xbfb8aa3b, v29
	v_exp_f32_e32 v9, v7
	v_rcp_f32_e32 v7, v0
	v_add_f32_e32 v0, 1.0, v8
	v_rcp_f32_e32 v8, v0
	v_add_f32_e32 v0, 1.0, v9
	v_rcp_f32_e32 v9, v0
	v_ashrrev_i32_e32 v41, 31, v40
	v_lshl_add_u64 v[4:5], v[40:41], 1, v[46:47]
	global_store_dwordx2 v[4:5], v[2:3], off
	v_pk_mul_f32 v[2:3], v[26:27], v[6:7]
	v_pk_mul_f32 v[4:5], v[28:29], v[8:9]
	v_pk_mul_f32 v[2:3], v[10:11], v[2:3]
	v_pk_mul_f32 v[4:5], v[12:13], v[4:5]
	v_mul_f32_e32 v0, 0xbfb8aa3b, v30
	v_cvt_pk_bf16_f32 v2, v2, v3
	v_cvt_pk_bf16_f32 v3, v4, v5
	v_exp_f32_e32 v0, v0
	v_mul_f32_e32 v4, 0xbfb8aa3b, v31
	v_exp_f32_e32 v7, v4
	v_or_b32_e32 v42, 16, v66
	v_add_f32_e32 v0, 1.0, v0
	v_rcp_f32_e32 v6, v0
	v_add_f32_e32 v0, 1.0, v7
	v_mul_f32_e32 v7, 0xbfb8aa3b, v32
	v_exp_f32_e32 v8, v7
	v_mul_f32_e32 v7, 0xbfb8aa3b, v33
	v_exp_f32_e32 v9, v7
	v_rcp_f32_e32 v7, v0
	v_add_f32_e32 v0, 1.0, v8
	v_rcp_f32_e32 v8, v0
	v_add_f32_e32 v0, 1.0, v9
	v_rcp_f32_e32 v9, v0
	v_ashrrev_i32_e32 v43, 31, v42
	v_lshl_add_u64 v[4:5], v[42:43], 1, v[46:47]
	v_or_b32_e32 v44, 24, v66
	global_store_dwordx2 v[4:5], v[2:3], off
	v_pk_mul_f32 v[2:3], v[30:31], v[6:7]
	v_pk_mul_f32 v[4:5], v[32:33], v[8:9]
	v_ashrrev_i32_e32 v45, 31, v44
	v_pk_mul_f32 v[2:3], v[14:15], v[2:3]
	v_pk_mul_f32 v[4:5], v[16:17], v[4:5]
	v_cvt_pk_bf16_f32 v2, v2, v3
	v_cvt_pk_bf16_f32 v3, v4, v5
	v_lshl_add_u64 v[4:5], v[44:45], 1, v[46:47]
	global_store_dwordx2 v[4:5], v[2:3], off
	s_branch .LBB0_843
